# attention tile loop: the next tile's four K-fragment LDS reads issued at the end of the current tile into dedicated registers (QK MFMAs no longer wait on LDS), on top of v34
# speedup vs baseline: 1.0098x; 1.0056x over previous
; #define LAS __attribute__((address_space(3)))
; __global__ void __launch_bounds__(NTHR, 2) hybrid_fwd(Args a) {
;     extern __shared__ __attribute__((aligned(16))) unsigned char lds_raw[];
;     LAS unsigned char* lds = (LAS unsigned char*)lds_raw;
;     const int tid = threadIdx.x, lane = tid & 63, wave = __builtin_amdgcn_readfirstlane(tid >> 6);
;     const int G = gridDim.x, bx = blockIdx.x;
;     const int vcu = (G % 8 == 0) ? (bx % 8) * (G / 8) + bx / 8 : bx;
;     const int gw = vcu * NWAVES + wave, NGW = G * NWAVES;
;     unsigned char* ws = a.ws;
;     float* MOD = (float*)(ws + WS_MOD); float* SWp = (float*)(ws + WS_SW); float* SSQ = (float*)(ws + WS_SSQ);
;     bf16_t* WAB = (bf16_t*)(ws + WS_WAB); bf16_t* WOAB = (bf16_t*)(ws + WS_WOAB); bf16_t* WC = (bf16_t*)(ws + WS_WC); bf16_t* WOC = (bf16_t*)(ws + WS_WOC);
;     bf16_t* H0 = (bf16_t*)(ws + WS_H0); bf16_t* Y = (bf16_t*)(ws + WS_Y);
;     bf16_t* Ub = (bf16_t*)(ws + WS_U); bf16_t* Gb = (bf16_t*)(ws + WS_G); bf16_t* UZb = (bf16_t*)(ws + WS_UZ); bf16_t* Vb = (bf16_t*)(ws + WS_V);
;     bf16_t* X1 = (bf16_t*)(ws + WS_X1); bf16_t* H1 = (bf16_t*)(ws + WS_H1);
;     bf16_t* Qb = (bf16_t*)(ws + WS_Q); bf16_t* Kb = (bf16_t*)(ws + WS_K); bf16_t* Zb = (bf16_t*)(ws + WS_Z); bf16_t* VTb = (bf16_t*)(ws + WS_VT); bf16_t* OZb = (bf16_t*)(ws + WS_OZ);
;     const int lo = a.ph_lo, hi = a.ph_hi;
;     ...
;     volatile LAS unsigned* bst = (volatile LAS unsigned*)(lds + LDS_BYTES - 64);
;     if (tid < 4) bst[tid] = 0u;
;     __syncthreads();
;     XcdBarrier xbar; xbar.bar = (unsigned*)(ws + WS_CTL); xbar.x = 0; xbar.st = bst;
;     if (hi - lo > 1) xbar = xcd_barrier_post((unsigned*)(ws + WS_CTL), bst);
_Z10hybrid_fwd4Args:
	s_load_dwordx2 s[54:55], s[0:1], 0x88
	s_load_dword s3, s[0:1], 0x90
	s_add_u32 s4, s0, 0x90
	s_addc_u32 s5, s1, 0
	v_readfirstlane_b32 s8, v0
	v_writelane_b32 v239, s4, 0
	s_mov_b32 s78, s2
	s_mov_b32 s84, s2
	v_writelane_b32 v239, s5, 1
	s_waitcnt lgkmcnt(0)
	s_and_b32 s4, s3, 7
	s_cmp_lg_u32 s4, 0
	s_cbranch_scc0 .LBB0_31
	s_load_dwordx2 s[52:53], s[0:1], 0x80
	v_cmp_gt_u32_e32 vcc, 4, v0
	s_and_saveexec_b64 s[4:5], vcc

; __device__ __forceinline__ unsigned xb_ld(unsigned* p)              { return __hip_atomic_load(p, __ATOMIC_RELAXED, __HIP_MEMORY_SCOPE_AGENT); }
; #define SEAM(k) do { if (IN(k) && IN((k) + 1)) xcd_barrier(xbar); } while (0)
; __device__ __forceinline__ void xcd_barrier_complete(unsigned* bar, unsigned x, unsigned& nloc, unsigned& nx) {
;     const unsigned G = gridDim.x * gridDim.y * gridDim.z;
;     unsigned sum, cnt, mine, sp = 0u;
;     for (;;) {
;         sum = 0u; cnt = 0u; mine = 0u;
; #pragma unroll
;         for (unsigned j = 0; j < 16; ++j) { const unsigned c = xb_ld(&bar[XB_XCNT(j)]); sum += c; cnt += (c > 0u) ? 1u : 0u; mine = (j == x) ? c : mine; }
; __device__ __forceinline__ void xcd_barrier(const XcdBarrier& b) {
;     asm volatile("s_waitcnt vmcnt(0)" ::: "memory");
;     __syncthreads();
;     if (threadIdx.x == 0) {
;         unsigned* bar = b.bar;
;         __builtin_amdgcn_s_waitcnt(0);
;         unsigned nloc = b.st[0], nx = b.st[1];
;         if (nloc == 0u) { xcd_barrier_complete(bar, b.x, nloc, nx); b.st[0] = nloc; b.st[1] = nx; }
; __global__ void __launch_bounds__(NTHR, 2) hybrid_fwd(Args a) {
;     ...
;     SEAM(1);
.LBB0_19:
	s_or_b64 exec, exec, s[18:19]
	s_cmp_gt_i32 s55, 1
	s_cselect_b64 s[0:1], -1, 0
	s_and_b64 vcc, exec, s[0:1]
	s_cbranch_vccz .LBB0_46
	s_waitcnt vmcnt(0)
	v_cmp_eq_u32_e32 vcc, 0, v0
	s_barrier
	s_and_saveexec_b64 s[4:5], vcc
	s_cbranch_execz .LBB0_45
	s_add_i32 s6, 0, 0x23fc0
	v_mov_b32_e32 v1, s6
	s_waitcnt vmcnt(0) expcnt(0) lgkmcnt(0)
	ds_read_b32 v2, v1
	s_add_i32 s6, 0, 0x23fc4
	v_mov_b32_e32 v1, s6
	ds_read_b32 v1, v1
	s_waitcnt lgkmcnt(1)
	v_cmp_ne_u32_e32 vcc, 0, v2
	s_cbranch_vccnz .LBB0_37
	v_readlane_b32 s6, v239, 0
	v_readlane_b32 s7, v239, 1
	s_load_dwordx2 s[10:11], s[6:7], 0x4
	s_add_u32 s6, s52, 0x1000
	s_addc_u32 s7, s53, 0
	s_add_u32 s8, s52, 0x1100
	s_addc_u32 s9, s53, 0
	s_waitcnt lgkmcnt(0)
	s_mul_i32 s24, s10, s3
	s_add_u32 s10, s52, 0x1200
	s_mul_i32 s24, s24, s11
	s_addc_u32 s11, s53, 0
	s_add_u32 s12, s52, 0x1300
	s_addc_u32 s13, s53, 0
	s_mov_b32 s25, 1
	v_mov_b32_e32 v17, 0
	s_branch .LBB0_24

; #define SEAM(k) do { if (IN(k) && IN((k) + 1)) xcd_barrier(xbar); } while (0)
; __device__ __forceinline__ void xcd_barrier(const XcdBarrier& b) {
;     asm volatile("s_waitcnt vmcnt(0)" ::: "memory");
;     __syncthreads();
;     if (threadIdx.x == 0) {
;         unsigned* bar = b.bar;
;         __builtin_amdgcn_s_waitcnt(0);
;         unsigned nloc = b.st[0], nx = b.st[1];
;         if (nloc == 0u) { xcd_barrier_complete(bar, b.x, nloc, nx); b.st[0] = nloc; b.st[1] = nx; }
; __global__ void __launch_bounds__(NTHR, 2) hybrid_fwd(Args a) {
;     ...
;     SEAM(2);
.LBB0_128:
	s_cmp_gt_i32 s55, 2
	s_cselect_b64 s[10:11], -1, 0
	s_and_b64 s[0:1], s[0:1], s[10:11]
	s_andn2_b64 vcc, exec, s[0:1]
	s_cbranch_vccnz .LBB0_178
	s_waitcnt vmcnt(0)
	v_cmp_eq_u32_e32 vcc, 0, v0
	s_waitcnt lgkmcnt(0)
	s_barrier
	s_and_saveexec_b64 s[0:1], vcc
	s_cbranch_execz .LBB0_177
	s_add_i32 s6, 0, 0x23fc0
	v_mov_b32_e32 v1, s6
	s_waitcnt vmcnt(0) expcnt(0) lgkmcnt(0)
	ds_read_b32 v3, v1
	s_add_i32 s6, 0, 0x23fc4
	v_mov_b32_e32 v1, s6
	ds_read_b32 v1, v1
	s_waitcnt lgkmcnt(1)
	v_cmp_ne_u32_e32 vcc, 0, v3
	s_cbranch_vccnz .LBB0_145
	v_readlane_b32 s6, v239, 0
	v_readlane_b32 s7, v239, 1
	s_load_dwordx2 s[14:15], s[6:7], 0x4
	s_add_u32 s6, s52, 0x1000
	s_addc_u32 s7, s53, 0
	s_add_u32 s12, s52, 0x1100
	s_addc_u32 s13, s53, 0
	s_waitcnt lgkmcnt(0)
	s_mul_i32 s35, s14, s3
	s_add_u32 s14, s52, 0x1200
	s_mul_i32 s35, s35, s15
	s_addc_u32 s15, s53, 0
	s_add_u32 s18, s52, 0x1300
	s_addc_u32 s19, s53, 0
	s_mov_b32 s36, 1
	v_mov_b32_e32 v17, 0
	s_branch .LBB0_133

; __device__ __forceinline__ unsigned xb_ld(unsigned* p)              { return __hip_atomic_load(p, __ATOMIC_RELAXED, __HIP_MEMORY_SCOPE_AGENT); }
; __device__ __forceinline__ unsigned xb_add(unsigned* p, unsigned v) { return __hip_atomic_fetch_add(p, v, __ATOMIC_RELAXED, __HIP_MEMORY_SCOPE_AGENT); }
; __device__ __forceinline__ void xcd_barrier_complete(unsigned* bar, unsigned x, unsigned& nloc, unsigned& nx) {
;     const unsigned G = gridDim.x * gridDim.y * gridDim.z;
;     unsigned sum, cnt, mine, sp = 0u;
;     for (;;) {
;         sum = 0u; cnt = 0u; mine = 0u;
; #pragma unroll
;         for (unsigned j = 0; j < 16; ++j) { const unsigned c = xb_ld(&bar[XB_XCNT(j)]); sum += c; cnt += (c > 0u) ? 1u : 0u; mine = (j == x) ? c : mine; }
;         if (sum == G) break;
; __device__ __forceinline__ void xcd_barrier(const XcdBarrier& b) {
;     asm volatile("s_waitcnt vmcnt(0)" ::: "memory");
;     __syncthreads();
;     if (threadIdx.x == 0) {
;         unsigned* bar = b.bar;
;         __builtin_amdgcn_s_waitcnt(0);
;         unsigned nloc = b.st[0], nx = b.st[1];
;         if (nloc == 0u) { xcd_barrier_complete(bar, b.x, nloc, nx); b.st[0] = nloc; b.st[1] = nx; }
;         const unsigned old = xb_add(&bar[XB_XSUB(b.x)], 1u);
.LBB0_217:
	s_cmp_gt_i32 s55, 3
	s_cselect_b64 s[0:1], -1, 0
	s_and_b64 s[10:11], s[10:11], s[0:1]
	s_andn2_b64 vcc, exec, s[10:11]
	s_cbranch_vccnz .LBB0_267
	s_waitcnt vmcnt(0)
	v_cmp_eq_u32_e32 vcc, 0, v0
	s_waitcnt vmcnt(0) lgkmcnt(0)
	s_barrier
	s_and_saveexec_b64 s[10:11], vcc
	s_cbranch_execz .LBB0_266
	s_add_i32 s12, 0, 0x23fc0
	v_mov_b32_e32 v1, s12
	s_waitcnt vmcnt(0) expcnt(0) lgkmcnt(0)
	ds_read_b32 v3, v1
	s_add_i32 s12, 0, 0x23fc4
	v_mov_b32_e32 v1, s12
	ds_read_b32 v1, v1
	s_waitcnt lgkmcnt(1)
	v_cmp_ne_u32_e32 vcc, 0, v3
	s_cbranch_vccnz .LBB0_234
	v_readlane_b32 s12, v239, 0
	v_readlane_b32 s13, v239, 1
	s_load_dwordx2 s[18:19], s[12:13], 0x4
	s_add_u32 s12, s52, 0x1000
	s_addc_u32 s13, s53, 0
	s_add_u32 s14, s52, 0x1100
	s_addc_u32 s15, s53, 0
	s_waitcnt lgkmcnt(0)
	s_mul_i32 s35, s18, s3
	s_add_u32 s18, s52, 0x1200
	s_mul_i32 s35, s35, s19
	s_addc_u32 s19, s53, 0
	s_add_u32 s22, s52, 0x1300
	s_addc_u32 s23, s53, 0
	s_mov_b32 s40, 1
	v_mov_b32_e32 v17, 0
	s_branch .LBB0_222

; __device__ __forceinline__ unsigned xb_ld(unsigned* p)              { return __hip_atomic_load(p, __ATOMIC_RELAXED, __HIP_MEMORY_SCOPE_AGENT); }
; __device__ __forceinline__ unsigned xb_add(unsigned* p, unsigned v) { return __hip_atomic_fetch_add(p, v, __ATOMIC_RELAXED, __HIP_MEMORY_SCOPE_AGENT); }
; __device__ __forceinline__ void xcd_barrier_complete(unsigned* bar, unsigned x, unsigned& nloc, unsigned& nx) {
;     const unsigned G = gridDim.x * gridDim.y * gridDim.z;
;     unsigned sum, cnt, mine, sp = 0u;
;     for (;;) {
;         sum = 0u; cnt = 0u; mine = 0u;
; #pragma unroll
;         for (unsigned j = 0; j < 16; ++j) { const unsigned c = xb_ld(&bar[XB_XCNT(j)]); sum += c; cnt += (c > 0u) ? 1u : 0u; mine = (j == x) ? c : mine; }
;         if (sum == G) break;
; __device__ __forceinline__ void xcd_barrier(const XcdBarrier& b) {
;     asm volatile("s_waitcnt vmcnt(0)" ::: "memory");
;     __syncthreads();
;     if (threadIdx.x == 0) {
;         unsigned* bar = b.bar;
;         __builtin_amdgcn_s_waitcnt(0);
;         unsigned nloc = b.st[0], nx = b.st[1];
;         if (nloc == 0u) { xcd_barrier_complete(bar, b.x, nloc, nx); b.st[0] = nloc; b.st[1] = nx; }
;         const unsigned old = xb_add(&bar[XB_XSUB(b.x)], 1u);
.LBB0_292:
	s_cmp_gt_i32 s55, 4
	s_cselect_b64 s[0:1], -1, 0
	s_and_b64 s[10:11], s[10:11], s[0:1]
	s_andn2_b64 vcc, exec, s[10:11]
	s_cbranch_vccnz .LBB0_342
	s_waitcnt vmcnt(0)
	v_cmp_eq_u32_e32 vcc, 0, v0
	s_waitcnt vmcnt(0) lgkmcnt(0)
	s_barrier
	s_and_saveexec_b64 s[10:11], vcc
	s_cbranch_execz .LBB0_341
	s_add_i32 s12, 0, 0x23fc0
	v_mov_b32_e32 v1, s12
	s_waitcnt vmcnt(0) expcnt(0) lgkmcnt(0)
	ds_read_b32 v3, v1
	s_add_i32 s12, 0, 0x23fc4
	v_mov_b32_e32 v1, s12
	ds_read_b32 v1, v1
	s_waitcnt lgkmcnt(1)
	v_cmp_ne_u32_e32 vcc, 0, v3
	s_cbranch_vccnz .LBB0_309
	v_readlane_b32 s12, v239, 0
	v_readlane_b32 s13, v239, 1
	s_load_dwordx2 s[18:19], s[12:13], 0x4
	s_add_u32 s12, s52, 0x1000
	s_addc_u32 s13, s53, 0
	s_add_u32 s14, s52, 0x1100
	s_addc_u32 s15, s53, 0
	s_waitcnt lgkmcnt(0)
	s_mul_i32 s30, s18, s3
	s_add_u32 s18, s52, 0x1200
	s_mul_i32 s30, s30, s19
	s_addc_u32 s19, s53, 0
	s_add_u32 s22, s52, 0x1300
	s_addc_u32 s23, s53, 0
	s_mov_b32 s31, 1
	v_mov_b32_e32 v17, 0
	s_branch .LBB0_297

; __device__ __forceinline__ unsigned xb_ld(unsigned* p)              { return __hip_atomic_load(p, __ATOMIC_RELAXED, __HIP_MEMORY_SCOPE_AGENT); }
; __device__ __forceinline__ unsigned xb_add(unsigned* p, unsigned v) { return __hip_atomic_fetch_add(p, v, __ATOMIC_RELAXED, __HIP_MEMORY_SCOPE_AGENT); }
; __device__ __forceinline__ void xcd_barrier_complete(unsigned* bar, unsigned x, unsigned& nloc, unsigned& nx) {
;     const unsigned G = gridDim.x * gridDim.y * gridDim.z;
;     unsigned sum, cnt, mine, sp = 0u;
;     for (;;) {
;         sum = 0u; cnt = 0u; mine = 0u;
; #pragma unroll
;         for (unsigned j = 0; j < 16; ++j) { const unsigned c = xb_ld(&bar[XB_XCNT(j)]); sum += c; cnt += (c > 0u) ? 1u : 0u; mine = (j == x) ? c : mine; }
;         if (sum == G) break;
; __device__ __forceinline__ void xcd_barrier(const XcdBarrier& b) {
;     asm volatile("s_waitcnt vmcnt(0)" ::: "memory");
;     __syncthreads();
;     if (threadIdx.x == 0) {
;         unsigned* bar = b.bar;
;         __builtin_amdgcn_s_waitcnt(0);
;         unsigned nloc = b.st[0], nx = b.st[1];
;         if (nloc == 0u) { xcd_barrier_complete(bar, b.x, nloc, nx); b.st[0] = nloc; b.st[1] = nx; }
;         const unsigned old = xb_add(&bar[XB_XSUB(b.x)], 1u);
.LBB0_385:
	s_cmp_gt_i32 s55, 6
	s_cselect_b64 s[0:1], -1, 0
	s_and_b64 s[8:9], s[12:13], s[0:1]
	s_andn2_b64 vcc, exec, s[8:9]
	s_cbranch_vccnz .LBB0_435
	s_waitcnt vmcnt(0)
	v_cmp_eq_u32_e32 vcc, 0, v0
	s_waitcnt vmcnt(0) lgkmcnt(0)
	s_barrier
	s_and_saveexec_b64 s[8:9], vcc
	s_cbranch_execz .LBB0_434
	s_add_i32 s12, 0, 0x23fc0
	v_mov_b32_e32 v1, s12
	s_waitcnt vmcnt(0) expcnt(0) lgkmcnt(0)
	ds_read_b32 v3, v1
	s_add_i32 s12, 0, 0x23fc4
	v_mov_b32_e32 v1, s12
	ds_read_b32 v1, v1
	s_waitcnt lgkmcnt(1)
	v_cmp_ne_u32_e32 vcc, 0, v3
	s_cbranch_vccnz .LBB0_402
	v_readlane_b32 s12, v239, 0
	v_readlane_b32 s13, v239, 1
	s_load_dwordx2 s[16:17], s[12:13], 0x4
	s_add_u32 s12, s52, 0x1000
	s_addc_u32 s13, s53, 0
	s_add_u32 s14, s52, 0x1100
	s_addc_u32 s15, s53, 0
	s_waitcnt lgkmcnt(0)
	s_mul_i32 s26, s16, s3
	s_add_u32 s16, s52, 0x1200
	s_mul_i32 s26, s26, s17
	s_addc_u32 s17, s53, 0
	s_add_u32 s18, s52, 0x1300
	s_addc_u32 s19, s53, 0
	s_mov_b32 s27, 1
	v_mov_b32_e32 v17, 0
	s_branch .LBB0_390

; __device__ __forceinline__ unsigned xb_ld(unsigned* p)              { return __hip_atomic_load(p, __ATOMIC_RELAXED, __HIP_MEMORY_SCOPE_AGENT); }
; __device__ __forceinline__ unsigned xb_add(unsigned* p, unsigned v) { return __hip_atomic_fetch_add(p, v, __ATOMIC_RELAXED, __HIP_MEMORY_SCOPE_AGENT); }
; __device__ __forceinline__ void xcd_barrier_complete(unsigned* bar, unsigned x, unsigned& nloc, unsigned& nx) {
;     const unsigned G = gridDim.x * gridDim.y * gridDim.z;
;     unsigned sum, cnt, mine, sp = 0u;
;     for (;;) {
;         sum = 0u; cnt = 0u; mine = 0u;
; #pragma unroll
;         for (unsigned j = 0; j < 16; ++j) { const unsigned c = xb_ld(&bar[XB_XCNT(j)]); sum += c; cnt += (c > 0u) ? 1u : 0u; mine = (j == x) ? c : mine; }
;         if (sum == G) break;
; __device__ __forceinline__ void xcd_barrier(const XcdBarrier& b) {
;     asm volatile("s_waitcnt vmcnt(0)" ::: "memory");
;     __syncthreads();
;     if (threadIdx.x == 0) {
;         unsigned* bar = b.bar;
;         __builtin_amdgcn_s_waitcnt(0);
;         unsigned nloc = b.st[0], nx = b.st[1];
;         if (nloc == 0u) { xcd_barrier_complete(bar, b.x, nloc, nx); b.st[0] = nloc; b.st[1] = nx; }
;         const unsigned old = xb_add(&bar[XB_XSUB(b.x)], 1u);
.LBB0_486:
	s_cmp_gt_i32 s55, 7
	s_cselect_b64 s[0:1], -1, 0
	s_and_b64 s[4:5], s[8:9], s[0:1]
	s_andn2_b64 vcc, exec, s[4:5]
	s_cbranch_vccnz .LBB0_536
	s_waitcnt vmcnt(0)
	v_cmp_eq_u32_e32 vcc, 0, v0
	s_waitcnt vmcnt(0) lgkmcnt(0)
	s_barrier
	s_and_saveexec_b64 s[4:5], vcc
	s_cbranch_execz .LBB0_535
	s_add_i32 s8, 0, 0x23fc0
	v_mov_b32_e32 v1, s8
	s_waitcnt vmcnt(0) expcnt(0) lgkmcnt(0)
	ds_read_b32 v3, v1
	s_add_i32 s8, 0, 0x23fc4
	v_mov_b32_e32 v1, s8
	ds_read_b32 v1, v1
	s_waitcnt lgkmcnt(1)
	v_cmp_ne_u32_e32 vcc, 0, v3
	s_cbranch_vccnz .LBB0_503
	v_readlane_b32 s8, v239, 0
	v_readlane_b32 s9, v239, 1
	s_load_dwordx2 s[12:13], s[8:9], 0x4
	s_add_u32 s8, s52, 0x1000
	s_addc_u32 s9, s53, 0
	s_add_u32 s10, s52, 0x1100
	s_addc_u32 s11, s53, 0
	s_waitcnt lgkmcnt(0)
	s_mul_i32 s22, s12, s3
	s_add_u32 s12, s52, 0x1200
	s_mul_i32 s22, s22, s13
	s_addc_u32 s13, s53, 0
	s_add_u32 s14, s52, 0x1300
	s_addc_u32 s15, s53, 0
	s_mov_b32 s23, 1
	v_mov_b32_e32 v17, 0
	s_branch .LBB0_491

; #define LAS __attribute__((address_space(3)))
; __device__ __forceinline__ void attn_phase(LAS unsigned char* lds, const bf16_t* Q, const bf16_t* Kb, const bf16_t* VT, const bf16_t* Zs, bf16_t* OZ, int vcu, int G) {
;     ...
;         ATT_DECODE(unit, h, rowbase, q0b, kw0)
;         const int qblk = unit & 31;
;         const int qb = 8 * qblk + w, q0 = 32 * qb;
;         bf16x8 qf[4];
;         { const bf16_t* qp = Q + (rowbase + q0 + ql) * D + h * 64 + 8 * hi;
; #pragma unroll
;           for (int kk = 0; kk < 4; ++kk) qf[kk] = *(const bf16x8*)(qp + 16 * kk); }
;         u32x2 zz[8];
;         { const bf16_t* zp = Zs + (rowbase + q0 + ql) * D + h * 64 + 4 * hi;
; #pragma unroll
;           for (int g4 = 0; g4 < 4; ++g4) { zz[g4] = *(const u32x2*)(zp + 8 * g4); zz[4 + g4] = *(const u32x2*)(zp + 32 + 8 * g4); } }
;         asm volatile("" ::: "memory");
; #pragma unroll
;         for (int i = 0; i < 6; ++i) { const int idx = tid + NTHR * i, r = idx >> 3, c = idx & 7;
;             *(LAS u32x4*)(KL + r * 128 + ((c ^ ((r >> 1) & 7)) << 4)) = sk[i]; }
; #pragma unroll
;         for (int i = 0; i < 6; ++i) { const int idx = tid + NTHR * i, d = idx / 48, ch = idx % 48;
;             { u32x4 v = sv[i]; const int gp = (2 * ch) ^ (d & 31);
;                 if (d & 1) { const u32x4 t = v; v.x = t.z; v.y = t.w; v.z = t.x; v.w = t.y; }
;                 *(LAS u32x4*)(VL + d * 768 + ((gp & ~1) << 3)) = v; } }
;         __syncthreads();
.LBB0_540:
	s_and_b32 s100, s84, 7
	s_bfe_u32 s99, s84, 0x20005
	s_lshl_b32 s99, s99, 3
	s_or_b32 s100, s100, s99
	s_bfe_u32 s99, s84, 0x20003
	s_lshl_b32 s99, s99, 5
	s_or_b32 s100, s100, s99
	s_bfe_u32 s99, s84, 0x20008
	s_lshl_b32 s99, s99, 7
	s_or_b32 s100, s100, s99
	s_bfe_u32 s99, s84, 0x10007
	s_lshl_b32 s99, s99, 9
	s_or_b32 s100, s100, s99
	s_ashr_i32 s74, s100, 9
	s_ashr_i32 s75, s74, 31
	s_and_b32 s58, s100, 31
	s_lshl_b64 s[78:79], s[74:75], 13
	s_lshl_b32 s74, s58, 3
	s_and_b32 s59, s100, 31
	s_lshl_b32 s81, s58, 8
	s_add_i32 s90, s74, s85
	s_lshl_b32 s91, s59, 3
	s_addk_i32 s81, 0xff80
	s_lshl_b32 s80, s90, 5
	s_add_u32 s74, s78, s80
	s_addc_u32 s75, s79, 0
	v_or_b32_e32 v190, s74, v142
	s_lshl_b32 s74, s100, 1
	s_and_b32 s92, s74, 0x3c0
	s_mov_b32 s72, s100
	s_lshl_b32 s76, s92, 1
	s_add_i32 s84, s84, s3
	s_and_b32 s101, s84, 7
	s_bfe_u32 s99, s84, 0x20005
	s_lshl_b32 s99, s99, 3
	s_or_b32 s101, s101, s99
	s_bfe_u32 s99, s84, 0x20003
	s_lshl_b32 s99, s99, 5
	s_or_b32 s101, s101, s99
	s_bfe_u32 s99, s84, 0x20008
	s_lshl_b32 s99, s99, 7
	s_or_b32 s101, s101, s99
	s_bfe_u32 s99, s84, 0x10007
	s_lshl_b32 s99, s99, 9
	s_or_b32 s101, s101, s99
	v_mov_b32_e32 v191, s75
	s_cmpk_gt_i32 s84, 0x3ff
	v_lshlrev_b64 v[2:3], 11, v[190:191]
	s_cselect_b64 s[74:75], -1, 0
	s_cmpk_lt_i32 s84, 0x400
	v_lshl_add_u64 v[4:5], s[64:65], 0, v[2:3]
	s_mov_b32 s77, s73
	v_lshl_add_u64 v[2:3], s[66:67], 0, v[2:3]
	s_cselect_b32 s72, s101, s72
	v_lshl_add_u64 v[4:5], v[4:5], 0, s[76:77]
	v_lshl_add_u64 v[2:3], v[2:3], 0, s[76:77]
	v_mov_b32_e32 v163, v145
	s_bfe_u32 s77, s72, 0x40005
	s_ashr_i32 s82, s72, 9
	s_lshl_b32 s72, s72, 8
	v_lshl_add_u64 v[4:5], v[4:5], 0, v[144:145]
	v_lshl_add_u64 v[2:3], v[2:3], 0, v[162:163]
	s_ashr_i32 s83, s82, 31
	s_and_b32 s72, s72, 0x1f00
	global_load_dwordx4 v[114:117], v[4:5], off
	global_load_dwordx4 v[118:121], v[4:5], off offset:32
	global_load_dwordx4 v[122:125], v[4:5], off offset:64
	global_load_dwordx4 v[126:129], v[4:5], off offset:96
	global_load_dwordx2 v[192:193], v[2:3], off
	global_load_dwordx2 v[186:187], v[2:3], off offset:16
	global_load_dwordx2 v[182:183], v[2:3], off offset:32
	global_load_dwordx2 v[178:179], v[2:3], off offset:48
	global_load_dwordx2 v[188:189], v[2:3], off offset:64
	global_load_dwordx2 v[184:185], v[2:3], off offset:80
	global_load_dwordx2 v[180:181], v[2:3], off offset:96
	global_load_dwordx2 v[176:177], v[2:3], off offset:112
	s_waitcnt vmcnt(17)
	v_cndmask_b32_e64 v5, v95, v97, s[48:49]
	v_cndmask_b32_e64 v4, v94, v96, s[48:49]
	v_cndmask_b32_e64 v3, v97, v95, s[48:49]
	v_cndmask_b32_e64 v2, v96, v94, s[48:49]
	s_lshl_b64 s[94:95], s[82:83], 13
	s_add_i32 s93, s72, 0xffffff80
	ds_write_b128 v206, v[66:69]
	ds_write_b128 v207, v[70:73]
	ds_write_b128 v206, v[74:77] offset:16384
	ds_write_b128 v208, v[78:81]
	ds_write_b128 v206, v[82:85] offset:32768
	ds_write_b128 v209, v[86:89]
	ds_write_b128 v210, v[2:5] offset:49152
	s_waitcnt vmcnt(16)
	v_cndmask_b32_e64 v5, v91, v93, s[4:5]
	v_cndmask_b32_e64 v4, v90, v92, s[4:5]
	v_cndmask_b32_e64 v3, v93, v91, s[4:5]
	v_cndmask_b32_e64 v2, v92, v90, s[4:5]
	s_cmp_lg_u32 s72, 0
	ds_write_b128 v211, v[2:5] offset:49152
	s_waitcnt vmcnt(15)
	v_cndmask_b32_e64 v5, v103, v105, s[6:7]
	v_cndmask_b32_e64 v4, v102, v104, s[6:7]
	v_cndmask_b32_e64 v3, v105, v103, s[6:7]
	v_cndmask_b32_e64 v2, v104, v102, s[6:7]
	s_cselect_b32 s96, s93, 0
	ds_write_b128 v212, v[2:5] offset:49152
	s_waitcnt vmcnt(14)
	v_cndmask_b32_e64 v5, v99, v101, s[8:9]
	v_cndmask_b32_e64 v4, v98, v100, s[8:9]
	v_cndmask_b32_e64 v3, v101, v99, s[8:9]
	v_cndmask_b32_e64 v2, v100, v98, s[8:9]
	s_ashr_i32 s97, s96, 31
	ds_write_b128 v213, v[2:5] offset:49152
	s_waitcnt vmcnt(13)
	v_cndmask_b32_e64 v5, v111, v113, s[10:11]
	v_cndmask_b32_e64 v4, v110, v112, s[10:11]
	v_cndmask_b32_e64 v3, v113, v111, s[10:11]
	v_cndmask_b32_e64 v2, v112, v110, s[10:11]
	s_add_u32 s94, s94, s96
	ds_write_b128 v214, v[2:5] offset:49152
	s_waitcnt vmcnt(12)
	v_cndmask_b32_e64 v5, v107, v109, s[12:13]
	v_cndmask_b32_e64 v4, v106, v108, s[12:13]
	v_cndmask_b32_e64 v3, v109, v107, s[12:13]
	v_cndmask_b32_e64 v2, v108, v106, s[12:13]
	s_addc_u32 s95, s95, s97
	ds_write_b128 v215, v[2:5] offset:49152
	s_lshl_b32 s72, s77, 7
	v_mov_b32_e32 v5, s95
	v_or_b32_e32 v4, s94, v146
	v_mov_b32_e32 v7, s95
	v_or_b32_e32 v6, s94, v148
	v_lshl_add_u64 v[2:3], v[158:159], 0, s[72:73]
	v_lshlrev_b64 v[4:5], 11, v[4:5]
	v_lshlrev_b64 v[6:7], 11, v[6:7]
	v_lshl_add_u64 v[4:5], v[2:3], 0, v[4:5]
	v_lshl_add_u64 v[6:7], v[2:3], 0, v[6:7]
	s_waitcnt lgkmcnt(0)
	s_barrier
; __device__ __forceinline__ void attn_phase(LAS unsigned char* lds, const bf16_t* Q, const bf16_t* Kb, const bf16_t* VT, const bf16_t* Zs, bf16_t* OZ, int vcu, int G) {
;     ...
;         { const int nu_ = unit + G < NU ? unit + G : unit; ATT_LOAD_STAGE(nu_); }
;         f32x16 o0, o1;
; #pragma unroll
;         for (int i = 0; i < 16; ++i) { o0[i] = 0.f; o1[i] = 0.f; }
;         float carry = 1.f;
	global_load_dwordx4 v[66:69], v[4:5], off
	global_load_dwordx4 v[70:73], v[6:7], off
	v_lshl_add_u64 v[4:5], s[94:95], 0, v[150:151]
	v_lshl_add_u64 v[6:7], s[94:95], 0, v[152:153]
	v_lshlrev_b64 v[4:5], 11, v[4:5]
	v_lshlrev_b64 v[6:7], 11, v[6:7]
	v_lshl_add_u64 v[4:5], v[2:3], 0, v[4:5]
	v_lshl_add_u64 v[6:7], v[2:3], 0, v[6:7]
	global_load_dwordx4 v[74:77], v[4:5], off
	global_load_dwordx4 v[78:81], v[6:7], off
	v_lshl_add_u64 v[4:5], s[94:95], 0, v[154:155]
	v_lshl_add_u64 v[6:7], s[94:95], 0, v[156:157]
	s_lshl_b32 s72, s77, 20
	s_lshl_b64 s[82:83], s[82:83], 14
	v_lshlrev_b64 v[4:5], 11, v[4:5]
	v_lshlrev_b64 v[6:7], 11, v[6:7]
	s_add_u32 s77, s68, s82
	v_lshl_add_u64 v[4:5], v[2:3], 0, v[4:5]
	v_lshl_add_u64 v[2:3], v[2:3], 0, v[6:7]
	s_addc_u32 s93, s69, s83
	s_lshl_b64 s[82:83], s[96:97], 1
	global_load_dwordx4 v[82:85], v[4:5], off
	global_load_dwordx4 v[86:89], v[2:3], off
	s_add_u32 s82, s77, s82
	v_or_b32_e32 v2, s72, v196
	s_addc_u32 s83, s93, s83
	v_lshlrev_b32_e32 v2, 1, v2
	v_mov_b32_e32 v3, v145
	v_or_b32_e32 v4, s72, v197
	v_lshl_add_u64 v[2:3], s[82:83], 0, v[2:3]
	v_mov_b32_e32 v165, v145
	v_lshlrev_b32_e32 v4, 1, v4
	v_mov_b32_e32 v5, v145
	v_lshl_add_u64 v[2:3], v[2:3], 0, v[164:165]
	v_lshl_add_u64 v[4:5], s[82:83], 0, v[4:5]
	v_mov_b32_e32 v167, v145
	v_lshl_add_u64 v[4:5], v[4:5], 0, v[166:167]
	global_load_dwordx4 v[94:97], v[2:3], off
	global_load_dwordx4 v[90:93], v[4:5], off
	v_or_b32_e32 v2, s72, v198
	v_lshlrev_b32_e32 v2, 1, v2
	v_mov_b32_e32 v3, v145
	v_or_b32_e32 v4, s72, v199
	v_lshl_add_u64 v[2:3], s[82:83], 0, v[2:3]
	v_mov_b32_e32 v169, v145
	v_lshlrev_b32_e32 v4, 1, v4
	v_mov_b32_e32 v5, v145
	v_lshl_add_u64 v[2:3], v[2:3], 0, v[168:169]
	v_lshl_add_u64 v[4:5], s[82:83], 0, v[4:5]
	v_mov_b32_e32 v171, v145
	v_lshl_add_u64 v[4:5], v[4:5], 0, v[170:171]
	global_load_dwordx4 v[102:105], v[2:3], off
	global_load_dwordx4 v[98:101], v[4:5], off
	v_or_b32_e32 v2, s72, v200
	v_lshlrev_b32_e32 v2, 1, v2
	v_mov_b32_e32 v3, v145
	v_or_b32_e32 v4, s72, v201
	v_lshl_add_u64 v[2:3], s[82:83], 0, v[2:3]
	v_mov_b32_e32 v173, v145
	v_lshlrev_b32_e32 v4, 1, v4
	v_mov_b32_e32 v5, v145
	v_lshl_add_u64 v[2:3], v[2:3], 0, v[172:173]
	v_lshl_add_u64 v[4:5], s[82:83], 0, v[4:5]
	v_mov_b32_e32 v175, v145
	v_lshl_add_u64 v[4:5], v[4:5], 0, v[174:175]
	global_load_dwordx4 v[110:113], v[2:3], off
	global_load_dwordx4 v[106:109], v[4:5], off
	s_cmp_lg_u32 s58, 0
	s_cselect_b32 s58, s81, 0
	s_cmp_lt_i32 s80, s58
	s_cbranch_scc1 .LBB0_552
	s_sub_i32 s72, s80, s58
	v_or_b32_e32 v2, s72, v142
	v_lshrrev_b32_e32 v27, 1, v2
	v_lshl_add_u32 v26, v2, 7, 0
	v_bitop3_b32 v2, v27, v1, 7 bitop3:0x6c
	v_lshl_add_u32 v2, v2, 4, v26
	ds_read_b128 v[2:5], v2
	s_lshr_b32 s77, s72, 2
	v_bitop3_b32 v6, s77, v142, v1 bitop3:0x36
	v_lshlrev_b32_e32 v30, 3, v6
	v_bitop3_b32 v6, v27, v143, 7 bitop3:0x6c
	v_lshl_add_u32 v6, v6, 4, v26
	ds_read_b128 v[18:21], v6
	v_or_b32_e32 v28, s77, v1
	s_waitcnt vmcnt(23) lgkmcnt(1)
	v_mfma_f32_32x32x16_bf16 v[2:17], v[2:5], v[114:117], 0
	v_bitop3_b32 v22, v28, v142, 2 bitop3:0x36
	v_lshlrev_b32_e32 v32, 3, v22
	v_bitop3_b32 v22, v28, v142, 4 bitop3:0x36
	v_lshlrev_b32_e32 v38, 3, v22
	v_bitop3_b32 v22, v27, v147, 7 bitop3:0x6c
	v_lshl_add_u32 v22, v22, 4, v26
	ds_read_b128 v[22:25], v22
	s_waitcnt vmcnt(22) lgkmcnt(1)
	v_mfma_f32_32x32x16_bf16 v[2:17], v[18:21], v[118:121], v[2:17]
	v_bitop3_b32 v18, v28, v142, 6 bitop3:0x36
	v_lshlrev_b32_e32 v39, 3, v18
	v_bitop3_b32 v18, v27, v149, 7 bitop3:0x6c
	v_lshl_add_u32 v18, v18, 4, v26
	ds_read_b128 v[26:29], v18
	v_add_u32_e32 v31, v202, v30
	v_add_u32_e32 v34, v202, v38
	s_waitcnt vmcnt(21) lgkmcnt(1)
	v_mfma_f32_32x32x16_bf16 v[2:17], v[22:25], v[122:125], v[2:17]
	v_add_u32_e32 v36, v202, v39
	v_add_u32_e32 v22, v203, v30
	v_add_u32_e32 v24, v203, v38
	v_add_u32_e32 v33, v202, v32
	ds_read_b64 v[18:19], v31 offset:49152
	ds_read_b64 v[20:21], v33 offset:49152
	ds_read_b64 v[34:35], v34 offset:49152
	ds_read_b64 v[36:37], v36 offset:49152
	v_add_u32_e32 v23, v203, v32
	v_add_u32_e32 v25, v203, v39
	s_waitcnt vmcnt(20) lgkmcnt(4)
	v_mfma_f32_32x32x16_bf16 v[2:17], v[26:29], v[126:129], v[2:17]
	ds_read_b64 v[42:43], v22 offset:24576
	ds_read_b64 v[44:45], v23 offset:24576
	ds_read_b64 v[38:39], v24 offset:24576
	ds_read_b64 v[40:41], v25 offset:24576
	v_and_b32_e32 v48, 64, v216
	v_add_u32_e32 v48, 64, v48
	s_mov_b64 s[80:81], 0
	s_nop 4
	v_min_f32_e64 v3, -v3, s98
	v_exp_f32_e32 v3, v3
	v_min_f32_e64 v4, -v4, s98
	v_exp_f32_e32 v24, v4
	v_add_f32_e32 v22, 1.0, v3
	v_min_f32_e64 v4, -v5, s98
	v_rcp_f32_e32 v22, v22
	v_exp_f32_e32 v5, v4
	v_add_f32_e32 v4, 1.0, v24
	v_mul_f32_e32 v3, v3, v22
	v_rcp_f32_e32 v25, v4
	v_cndmask_b32_e64 v4, 1.0, v3, s[16:17]
	v_add_f32_e32 v3, 1.0, v5
	v_min_f32_e64 v2, -v2, s98
	v_rcp_f32_e32 v3, v3
	v_exp_f32_e32 v2, v2
	v_mul_f32_e32 v24, v24, v25
	v_cndmask_b32_e64 v46, 1.0, v24, s[18:19]
	v_mul_f32_e32 v5, v5, v3
	v_cndmask_b32_e64 v24, 0, v3, s[20:21]
	v_min_f32_e64 v3, -v6, s98
	v_min_f32_e64 v6, -v7, s98
	v_add_f32_e32 v26, 1.0, v2
	v_exp_f32_e32 v3, v3
	v_rcp_f32_e32 v26, v26
	v_exp_f32_e32 v7, v6
	v_add_f32_e32 v6, 1.0, v3
	v_cndmask_b32_e64 v22, 0, v22, s[16:17]
	v_mul_f32_e32 v2, v2, v26
	v_cndmask_b32_e64 v23, 0, v26, s[14:15]
	v_rcp_f32_e32 v26, v6
	v_cndmask_b32_e64 v6, 1.0, v5, s[20:21]
	v_add_f32_e32 v5, 1.0, v7
	v_rcp_f32_e32 v5, v5
	v_mul_f32_e32 v3, v3, v26
	v_cndmask_b32_e64 v3, 1.0, v3, s[22:23]
	v_cndmask_b32_e64 v2, 1.0, v2, s[14:15]
	v_mul_f32_e32 v7, v7, v5
	v_cndmask_b32_e64 v27, 0, v5, s[24:25]
	v_min_f32_e64 v5, -v8, s98
	v_min_f32_e64 v8, -v9, s98
	v_exp_f32_e32 v5, v5
	v_exp_f32_e32 v8, v8
; __device__ __forceinline__ void attn_phase(LAS unsigned char* lds, const bf16_t* Q, const bf16_t* Kb, const bf16_t* VT, const bf16_t* Zs, bf16_t* OZ, int vcu, int G) {
;     ...
;         int kt = qb; bool done = false;
;     ...
;             ATT_TILE(true)
;             if (__all(carry < STOP)) { done = true; break; }
;         }
;     ...
;             ATT_TILE(false)
	v_cndmask_b32_e64 v28, 1.0, v7, s[24:25]
	v_add_f32_e32 v9, 1.0, v5
	v_rcp_f32_e32 v9, v9
	v_add_f32_e32 v7, 1.0, v8
	v_rcp_f32_e32 v7, v7
	v_mul_f32_e32 v3, v3, v28
	v_mul_f32_e32 v5, v5, v9
	v_cndmask_b32_e64 v30, 1.0, v5, s[26:27]
	v_mul_f32_e32 v5, v8, v7
	v_min_f32_e64 v8, -v11, s98
	v_cndmask_b32_e64 v31, 0, v7, s[28:29]
	v_min_f32_e64 v7, -v10, s98
	v_exp_f32_e32 v8, v8
	v_exp_f32_e32 v7, v7
	v_cndmask_b32_e64 v10, 1.0, v5, s[28:29]
	v_cndmask_b32_e64 v29, 0, v9, s[26:27]
	v_add_f32_e32 v5, 1.0, v8
	v_add_f32_e32 v9, 1.0, v7
	v_rcp_f32_e32 v5, v5
	v_rcp_f32_e32 v9, v9
	v_cndmask_b32_e64 v25, 0, v25, s[18:19]
	v_cndmask_b32_e64 v26, 0, v26, s[22:23]
	v_mul_f32_e32 v8, v8, v5
	v_cndmask_b32_e64 v51, 0, v5, s[34:35]
	v_min_f32_e64 v5, -v12, s98
	v_mul_f32_e32 v7, v7, v9
	v_cndmask_b32_e64 v50, 0, v9, s[30:31]
	v_min_f32_e64 v9, -v13, s98
	v_exp_f32_e32 v5, v5
	v_exp_f32_e32 v9, v9
	v_cndmask_b32_e64 v12, 1.0, v8, s[34:35]
	v_add_f32_e32 v11, 1.0, v5
	v_rcp_f32_e32 v11, v11
	v_add_f32_e32 v8, 1.0, v9
	v_rcp_f32_e32 v8, v8
	v_cndmask_b32_e64 v7, 1.0, v7, s[30:31]
	v_mul_f32_e32 v5, v5, v11
	v_cndmask_b32_e64 v52, 0, v11, s[36:37]
	v_cndmask_b32_e64 v11, 1.0, v5, s[36:37]
	v_mul_f32_e32 v5, v9, v8
	v_min_f32_e64 v9, -v15, s98
	v_exp_f32_e32 v9, v9
	v_cndmask_b32_e64 v15, 1.0, v5, s[38:39]
	v_cndmask_b32_e64 v13, 0, v8, s[38:39]
	v_min_f32_e64 v8, -v14, s98
	v_add_f32_e32 v5, 1.0, v9
	v_rcp_f32_e32 v5, v5
	v_exp_f32_e32 v8, v8
	v_mul_f32_e32 v7, v7, v12
	v_mul_f32_e32 v9, v9, v5
	v_cndmask_b32_e64 v32, 0, v5, s[42:43]
	v_min_f32_e64 v5, -v16, s98
	v_min_f32_e64 v16, -v17, s98
	v_exp_f32_e32 v5, v5
	v_exp_f32_e32 v16, v16
	v_add_f32_e32 v14, 1.0, v8
	v_add_f32_e32 v17, 1.0, v5
	v_rcp_f32_e32 v17, v17
	v_add_f32_e32 v33, 1.0, v16
	v_rcp_f32_e32 v33, v33
	v_rcp_f32_e32 v14, v14
	v_mul_f32_e32 v5, v5, v17
	v_cndmask_b32_e64 v47, 1.0, v5, s[44:45]
	v_mul_f32_e32 v5, v16, v33
	v_mul_f32_e32 v8, v8, v14
	v_cndmask_b32_e64 v16, 0, v33, s[46:47]
	v_cndmask_b32_e64 v33, 1.0, v5, s[46:47]
	v_xor_b32_e32 v5, 32, v216
	v_cndmask_b32_e64 v8, 1.0, v8, s[40:41]
	v_cndmask_b32_e64 v9, 1.0, v9, s[42:43]
	v_cmp_lt_i32_e32 vcc, v5, v48
	v_mul_f32_e32 v8, v8, v9
	v_mul_f32_e32 v48, v47, v33
	v_cndmask_b32_e32 v5, v216, v5, vcc
	v_lshlrev_b32_e32 v163, 2, v5
	v_mul_f32_e32 v8, v8, v48
	v_mov_b32_e32 v238, v8
	v_mov_b32_e32 v48, v8
	s_nop 1
	v_permlane32_swap_b32_e32 v238, v48
	s_nop 0
	v_cndmask_b32_e64 v48, v238, v48, s[0:1]
	v_mul_f32_e32 v49, v11, v15
	v_mul_f32_e32 v5, v30, v10
	v_mul_f32_e32 v7, v7, v49
	v_mul_f32_e32 v3, v3, v5
	v_mov_b32_e32 v238, v7
	v_mov_b32_e32 v53, v7
	s_nop 1
	v_permlane32_swap_b32_e32 v238, v53
	s_nop 0
	v_cndmask_b32_e64 v53, v238, v53, s[0:1]
	v_mov_b32_e32 v238, v3
	v_mov_b32_e32 v5, v3
	s_nop 1
	v_permlane32_swap_b32_e32 v238, v5
	s_nop 0
	v_cndmask_b32_e64 v5, v238, v5, s[0:1]
	s_waitcnt lgkmcnt(2)
	v_cndmask_b32_e64 v49, 1.0, v48, s[0:1]
	v_mul_f32_e32 v33, v33, v49
	v_mul_f32_e32 v47, v47, v33
	v_mul_f32_e32 v54, v9, v47
	v_mul_f32_e32 v57, v32, v47
	v_mul_f32_e32 v47, v8, v48
	s_waitcnt lgkmcnt(1)
	v_mul_f32_e32 v7, v7, v53
	v_pk_mul_f32 v[8:9], v[46:47], v[6:7]
	s_waitcnt lgkmcnt(0)
	v_pk_mul_f32 v[2:3], v[2:3], v[4:5]
	v_mul_f32_e32 v55, v16, v49
	v_pk_mul_f32 v[48:49], v[2:3], v[8:9]
	v_mov_b32_e32 v238, v48
	v_mov_b32_e32 v58, v48
	s_nop 1
	v_permlane32_swap_b32_e32 v238, v58
	s_nop 0
	v_cndmask_b32_e64 v58, v238, v58, s[0:1]
	v_mul_f32_e32 v2, v9, v5
	v_cndmask_b32_e64 v2, v9, v2, s[0:1]
	v_mul_f32_e32 v3, v10, v2
	v_mul_f32_e32 v8, v31, v2
	s_waitcnt lgkmcnt(0)
	v_mul_f32_e32 v2, v49, v58
	v_cndmask_b32_e64 v2, v49, v2, s[0:1]
	v_mul_f32_e32 v5, v30, v3
	v_mul_f32_e32 v9, v29, v3
	v_mul_f32_e32 v3, v6, v2
	v_mul_f32_e32 v6, v46, v3
	v_mul_f32_e32 v4, v4, v6
	v_mul_f32_e32 v10, v24, v2
	v_mul_f32_e32 v2, v22, v6
	v_mul_f32_e32 v6, v47, v53
	v_mul_f32_e32 v7, v28, v5
	v_cndmask_b32_e64 v6, v47, v6, s[0:1]
	v_mul_f32_e32 v5, v27, v5
	v_mul_f32_e32 v7, v26, v7
	v_mul_f32_e32 v3, v25, v3
	v_mul_f32_e32 v4, v23, v4
	v_mul_f32_e32 v47, v15, v6
	v_cndmask_b32_e64 v14, 0, v14, s[40:41]
	v_cndmask_b32_e64 v17, 0, v17, s[44:45]
	v_cvt_pk_bf16_f32 v2, v4, v2
	v_cvt_pk_bf16_f32 v3, v3, v10
	v_cvt_pk_bf16_f32 v4, v7, v5
	v_cvt_pk_bf16_f32 v5, v9, v8
	v_mul_f32_e32 v53, v11, v47
	v_mul_f32_e32 v56, v17, v33
	v_mfma_f32_32x32x16_bf16 v[18:33], v[18:21], v[2:5], 0
	v_mul_f32_e32 v46, v14, v54
	v_mul_f32_e32 v54, v12, v53
	v_mul_f32_e32 v59, v13, v6
	v_mfma_f32_32x32x16_bf16 v[2:17], v[42:45], v[2:5], 0
	v_mul_f32_e32 v43, v52, v47
	v_mul_f32_e32 v42, v51, v53
	v_mul_f32_e32 v44, v50, v54
	v_cvt_pk_bf16_f32 v42, v44, v42
	v_cvt_pk_bf16_f32 v43, v43, v59
	v_cvt_pk_bf16_f32 v44, v46, v57
	v_cvt_pk_bf16_f32 v45, v56, v55
	s_nop 1
	v_mfma_f32_32x32x16_bf16 v[18:33], v[34:37], v[42:45], v[18:33]
	v_mul_f32_e32 v34, v48, v58
	v_mul_f32_e32 v131, v34, v49
	v_cmp_gt_f32_e32 vcc, s88, v131
	s_cmp_eq_u64 vcc, exec
	v_mfma_f32_32x32x16_bf16 v[2:17], v[38:41], v[42:45], v[2:17]
	s_cbranch_scc1 .LBB0_553
	s_cmp_eq_u32 s90, 0
	s_cbranch_scc1 .LBB0_556
	s_lshl_b32 s72, s59, 8
	s_lshl_b32 s77, s59, 15
	s_sub_i32 s59, s72, 32
	v_add_u32_e32 v34, s72, v204
	s_lshl_b32 s72, s58, 7
	s_sub_i32 s72, s77, s72
	s_add_i32 s93, s86, s91
	v_subrev_u32_e32 v165, s58, v34
	v_add_u32_e32 v167, s72, v205
	s_sub_i32 s77, s59, s58
	s_nop 7
	v_mov_b64_e32 v[34:35], v[2:3]
	v_mov_b64_e32 v[36:37], v[4:5]
	v_mov_b64_e32 v[38:39], v[6:7]
	v_mov_b64_e32 v[40:41], v[8:9]
	v_mov_b64_e32 v[42:43], v[10:11]
	v_mov_b64_e32 v[44:45], v[12:13]
	v_mov_b64_e32 v[46:47], v[14:15]
	v_mov_b64_e32 v[48:49], v[16:17]
	v_mov_b64_e32 v[50:51], v[18:19]
	v_mov_b64_e32 v[52:53], v[20:21]
	v_mov_b64_e32 v[54:55], v[22:23]
	v_mov_b64_e32 v[56:57], v[24:25]
	v_mov_b64_e32 v[58:59], v[26:27]
	v_mov_b64_e32 v[60:61], v[28:29]
	v_mov_b64_e32 v[62:63], v[30:31]
	v_mov_b64_e32 v[64:65], v[32:33]
	v_add_u32_e32 v255, s87, v165
	v_lshrrev_b32_e32 v255, 1, v255
	v_bitop3_b32 v240, v255, v1, 7 bitop3:0x6c
	v_lshl_add_u32 v240, v240, 4, v167
	ds_read_b128 v[240:243], v240
	v_bitop3_b32 v244, v255, v143, 7 bitop3:0x6c
	v_lshl_add_u32 v244, v244, 4, v167
	ds_read_b128 v[244:247], v244
	v_bitop3_b32 v248, v255, v147, 7 bitop3:0x6c
	v_lshl_add_u32 v248, v248, 4, v167
	ds_read_b128 v[248:251], v248
	v_bitop3_b32 v252, v255, v149, 7 bitop3:0x6c
	v_lshl_add_u32 v252, v252, 4, v167
	ds_read_b128 v[252:255], v252
	s_branch .LBB0_545

; __device__ __forceinline__ void attn_phase(LAS unsigned char* lds, const bf16_t* Q, const bf16_t* Kb, const bf16_t* VT, const bf16_t* Zs, bf16_t* OZ, int vcu, int G) {
;     ...
;         int kt = qb; bool done = false;
;     ...
;             ATT_TILE(true)
;             if (__all(carry < STOP)) { done = true; break; }
;         }
;     ...
;             ATT_TILE(false)
;             if (__all(carry < STOP)) break;
.LBB0_545:
	s_add_i32 s72, s87, s59
	v_mov_b32_e32 v195, v131
	s_cmp_lt_i32 s72, s58
	s_mov_b32 s72, s93
	s_cbranch_scc1 .LBB0_544
	s_add_i32 s80, s87, s77
	s_lshr_b32 s80, s80, 2
	v_bitop3_b32 v6, s80, v142, v1 bitop3:0x36
	v_lshlrev_b32_e32 v28, 3, v6
	v_or_b32_e32 v27, s80, v1
	s_waitcnt lgkmcnt(0)
	v_mfma_f32_32x32x16_bf16 v[2:17], v[240:243], v[114:117], 0
	v_bitop3_b32 v22, v27, v142, 2 bitop3:0x36
	v_lshlrev_b32_e32 v30, 3, v22
	v_bitop3_b32 v22, v27, v142, 4 bitop3:0x36
	v_lshlrev_b32_e32 v32, 3, v22
	s_waitcnt lgkmcnt(1)
	v_mfma_f32_32x32x16_bf16 v[2:17], v[244:247], v[118:121], v[2:17]
	v_bitop3_b32 v18, v27, v142, 6 bitop3:0x36
	v_lshlrev_b32_e32 v27, 3, v18
	v_add_u32_e32 v29, v202, v28
	v_add_u32_e32 v132, v202, v27
	s_waitcnt lgkmcnt(1)
	v_mfma_f32_32x32x16_bf16 v[2:17], v[248:251], v[122:125], v[2:17]
	v_add_u32_e32 v22, v203, v28
	v_add_u32_e32 v31, v202, v30
	v_add_u32_e32 v33, v202, v32
	ds_read_b64 v[138:139], v29 offset:49152
	ds_read_b64 v[140:141], v31 offset:49152
	ds_read_b64 v[130:131], v33 offset:49152
	ds_read_b64 v[132:133], v132 offset:49152
	v_add_u32_e32 v23, v203, v30
	v_add_u32_e32 v24, v203, v32
	v_add_u32_e32 v25, v203, v27
	s_waitcnt lgkmcnt(4)
	v_mfma_f32_32x32x16_bf16 v[2:17], v[252:255], v[126:129], v[2:17]
	ds_read_b64 v[218:219], v22 offset:24576
	ds_read_b64 v[220:221], v23 offset:24576
	ds_read_b64 v[134:135], v24 offset:24576
	ds_read_b64 v[136:137], v25 offset:24576
	s_add_i32 s90, s90, -1
	s_nop 6
	v_min_f32_e64 v3, -v3, s98
	v_exp_f32_e32 v3, v3
	v_min_f32_e64 v5, -v5, s98
	v_min_f32_e64 v4, -v4, s98
	v_add_f32_e32 v19, 1.0, v3
	v_exp_f32_e32 v194, v5
	v_min_f32_e64 v5, -v6, s98
	v_rcp_f32_e32 v169, v19
	v_exp_f32_e32 v4, v4
	v_exp_f32_e32 v6, v5
	v_min_f32_e64 v5, -v7, s98
	v_exp_f32_e32 v7, v5
	v_mul_f32_e32 v20, v3, v169
	v_add_f32_e32 v3, 1.0, v4
	v_rcp_f32_e32 v22, v3
	v_add_f32_e32 v3, 1.0, v194
	v_rcp_f32_e32 v24, v3
	v_add_f32_e32 v3, 1.0, v6
	v_rcp_f32_e32 v26, v3
	v_add_f32_e32 v3, 1.0, v7
	v_rcp_f32_e32 v27, v3
	v_min_f32_e64 v3, -v8, s98
	v_exp_f32_e32 v8, v3
	v_min_f32_e64 v3, -v9, s98
	v_exp_f32_e32 v9, v3
	v_add_f32_e32 v3, 1.0, v8
	v_rcp_f32_e32 v28, v3
	v_min_f32_e64 v5, -v12, s98
	v_add_f32_e32 v3, 1.0, v9
	v_rcp_f32_e32 v29, v3
	v_min_f32_e64 v3, -v10, s98
	v_exp_f32_e32 v10, v3
	v_min_f32_e64 v3, -v11, s98
	v_exp_f32_e32 v11, v5
	v_min_f32_e64 v5, -v13, s98
	v_exp_f32_e32 v31, v5
	v_min_f32_e64 v5, -v14, s98
	v_exp_f32_e32 v30, v3
	v_exp_f32_e32 v12, v5
	v_min_f32_e64 v5, -v15, s98
	v_exp_f32_e32 v14, v5
	v_min_f32_e64 v5, -v16, s98
	v_add_f32_e32 v3, 1.0, v10
	v_rcp_f32_e32 v226, v3
	v_add_f32_e32 v3, 1.0, v30
	v_exp_f32_e32 v13, v5
	v_min_f32_e64 v5, -v17, s98
	v_rcp_f32_e32 v228, v3
	v_add_f32_e32 v3, 1.0, v11
	v_rcp_f32_e32 v227, v3
	v_add_f32_e32 v3, 1.0, v31
	v_exp_f32_e32 v15, v5
	v_rcp_f32_e32 v229, v3
	v_add_f32_e32 v3, 1.0, v12
	v_rcp_f32_e32 v230, v3
	v_add_f32_e32 v3, 1.0, v14
	v_rcp_f32_e32 v16, v3
	v_add_f32_e32 v3, 1.0, v13
	v_rcp_f32_e32 v231, v3
	v_add_f32_e32 v3, 1.0, v15
	v_rcp_f32_e32 v17, v3
	v_min_f32_e64 v2, -v2, s98
	v_exp_f32_e32 v2, v2
	v_pk_mul_f32 v[12:13], v[12:13], v[230:231]
	v_pk_mul_f32 v[14:15], v[14:15], v[16:17]
	v_pk_mul_f32 v[6:7], v[6:7], v[26:27]
	v_pk_mul_f32 v[224:225], v[12:13], v[14:15]
	v_add_f32_e32 v18, 1.0, v2
	v_mul_f32_e32 v3, v224, v225
	v_mov_b32_e32 v238, v3
	v_mov_b32_e32 v5, v3
	s_nop 1
	v_permlane32_swap_b32_e32 v238, v5
	s_nop 0
	v_cndmask_b32_e64 v5, v238, v5, s[0:1]
	v_rcp_f32_e32 v18, v18
	v_pk_mul_f32 v[8:9], v[8:9], v[28:29]
	v_pk_mul_f32 v[10:11], v[10:11], v[226:227]
	v_pk_mul_f32 v[232:233], v[30:31], v[228:229]
	v_pk_mul_f32 v[32:33], v[6:7], v[6:7] op_sel_hi:[0,1]
	v_pk_mul_f32 v[222:223], v[8:9], v[8:9] op_sel_hi:[0,1]
	v_pk_mul_f32 v[30:31], v[10:11], v[232:233]
	s_waitcnt lgkmcnt(0)
	v_mul_f32_e32 v25, v3, v5
	v_pk_mul_f32 v[30:31], v[30:31], v[30:31] op_sel:[0,1] op_sel_hi:[1,0]
	v_mov_b32_e32 v3, v33
	v_mov_b32_e32 v19, v223
	v_mov_b32_e32 v238, v30
	v_mov_b32_e32 v23, v30
	s_nop 1
	v_permlane32_swap_b32_e32 v238, v23
	s_nop 0
	v_cndmask_b32_e64 v23, v238, v23, s[0:1]
	v_pk_mul_f32 v[2:3], v[2:3], v[18:19]
	v_mul_f32_e32 v6, v195, v5
	v_mov_b32_e32 v238, v3
	v_mov_b32_e32 v21, v3
	s_nop 1
	v_permlane32_swap_b32_e32 v238, v21
	s_nop 0
	v_cndmask_b32_e64 v21, v238, v21, s[0:1]
	v_cndmask_b32_e64 v225, v195, v6, s[0:1]
	v_mul_f32_e32 v224, v15, v225
	v_mul_f32_e32 v13, v13, v224
	v_mov_b32_e32 v5, v30
	v_mul_f32_e32 v12, v14, v13
	v_pk_mul_f32 v[14:15], v[194:195], v[24:25]
	s_waitcnt lgkmcnt(1)
	v_pk_mul_f32 v[4:5], v[4:5], v[22:23]
	v_mov_b32_e32 v234, v231
	v_mov_b32_e32 v235, v17
	v_mov_b32_e32 v231, v16
	v_pk_mul_f32 v[16:17], v[4:5], v[14:15]
	s_waitcnt lgkmcnt(0)
	v_pk_mul_f32 v[2:3], v[2:3], v[20:21]
	v_mul_f32_e32 v10, v15, v23
	v_pk_mul_f32 v[236:237], v[2:3], v[16:17]
	v_mov_b32_e32 v238, v236
	v_mov_b32_e32 v171, v236
	s_nop 1
	v_permlane32_swap_b32_e32 v238, v171
	s_nop 0
	v_cndmask_b32_e64 v171, v238, v171, s[0:1]
	v_mul_f32_e32 v2, v17, v21
	v_cndmask_b32_e64 v3, v17, v2, s[0:1]
	v_mul_f32_e32 v2, v9, v3
	v_pk_mul_f32 v[16:17], v[28:29], v[2:3]
	v_mul_f32_e32 v3, v8, v2
	s_waitcnt lgkmcnt(0)
	v_mul_f32_e32 v5, v237, v171
	v_mul_f32_e32 v2, v7, v3
	v_cndmask_b32_e64 v7, v237, v5, s[0:1]
	v_mul_f32_e32 v6, v14, v7
	v_mul_f32_e32 v5, v4, v6
	v_pk_mul_f32 v[2:3], v[26:27], v[2:3]
	v_mov_b32_e32 v23, v24
	v_mul_f32_e32 v4, v20, v5
	v_mov_b32_e32 v19, v169
	v_pk_mul_f32 v[234:235], v[234:235], v[224:225]
	v_pk_mul_f32 v[8:9], v[22:23], v[6:7]
	v_pk_mul_f32 v[4:5], v[18:19], v[4:5]
	v_cvt_pk_bf16_f32 v224, v2, v3
	v_cndmask_b32_e64 v3, v15, v10, s[0:1]
	v_cvt_pk_bf16_f32 v222, v4, v5
	v_cvt_pk_bf16_f32 v223, v8, v9
	v_cvt_pk_bf16_f32 v225, v16, v17
	v_mul_f32_e32 v2, v233, v3
	v_mov_b32_e32 v4, v227
	v_mov_b32_e32 v5, v229
	v_mfma_f32_32x32x16_bf16 v[50:65], v[138:141], v[222:225], v[50:65]
	v_mul_f32_e64 v140, v230, v12
	v_mul_f32_e64 v141, v231, v13
	v_mul_f32_e64 v230, v4, v2
	v_mul_f32_e64 v231, v5, v3
	v_mul_f32_e32 v139, v11, v2
	v_mul_f32_e32 v138, v232, v139
	v_mov_b32_e32 v227, v228
	v_pk_mul_f32 v[138:139], v[226:227], v[138:139]
	v_cvt_pk_bf16_f32 v140, v140, v141
	v_mfma_f32_32x32x16_bf16 v[34:49], v[218:221], v[222:225], v[34:49]
	v_cvt_pk_bf16_f32 v138, v138, v139
	v_cvt_pk_bf16_f32 v139, v230, v231
	v_cvt_pk_bf16_f32 v141, v234, v235
	s_nop 1
	v_mfma_f32_32x32x16_bf16 v[50:65], v[130:133], v[138:141], v[50:65]
	v_mul_f32_e32 v130, v236, v171
	v_mul_f32_e32 v131, v130, v237
	v_cmp_gt_f32_e32 vcc, s88, v131
	s_cmp_lg_u64 vcc, exec
	v_mfma_f32_32x32x16_bf16 v[34:49], v[134:137], v[138:141], v[34:49]
	s_cbranch_scc0 .LBB0_548
; #define LAS __attribute__((address_space(3)))
; __device__ __forceinline__ void attn_load_k(bf16x8 (&kf)[4], bool in_lds, LAS unsigned char* KL, int kl0, const bf16_t* kg, int ql, int hi) {
;     if (in_lds) { const int r = kl0 + ql; LAS unsigned char* rp = KL + r * 128; const int sw = (r >> 1) & 7;
; #pragma unroll
;         for (int kk = 0; kk < 4; ++kk) kf[kk] = *(const LAS bf16x8*)(rp + (((2 * kk + hi) ^ sw) << 4));
; __device__ __forceinline__ void attn_phase(LAS unsigned char* lds, const bf16_t* Q, const bf16_t* Kb, const bf16_t* VT, const bf16_t* Zs, bf16_t* OZ, int vcu, int G) {
;     ...
;             ATT_TILE(false)
;             if (__all(carry < STOP)) break;
	s_add_i32 s93, s72, -1
	s_sub_i32 s77, s77, 32
	s_sub_i32 s59, s59, 32
	s_cmp_lt_i32 s93, 2
	s_mov_b32 s94, -1
	v_subrev_u32_e32 v165, 32, v165
	v_add_u32_e32 v167, 0xfffff000, v167
	s_cselect_b64 s[80:81], -1, 0
	s_mov_b64 s[82:83], 0
	s_and_b64 vcc, exec, s[80:81]
	v_add_u32_e32 v255, s87, v165
	v_lshrrev_b32_e32 v255, 1, v255
	v_bitop3_b32 v240, v255, v1, 7 bitop3:0x6c
	v_lshl_add_u32 v240, v240, 4, v167
	ds_read_b128 v[240:243], v240
	v_bitop3_b32 v244, v255, v143, 7 bitop3:0x6c
	v_lshl_add_u32 v244, v244, 4, v167
	ds_read_b128 v[244:247], v244
	v_bitop3_b32 v248, v255, v147, 7 bitop3:0x6c
	v_lshl_add_u32 v248, v248, 4, v167
	ds_read_b128 v[248:251], v248
	v_bitop3_b32 v252, v255, v149, 7 bitop3:0x6c
	v_lshl_add_u32 v252, v252, 4, v167
	ds_read_b128 v[252:255], v252
	s_cbranch_vccz .LBB0_545
	s_branch .LBB0_549

; __device__ __forceinline__ unsigned xb_ld(unsigned* p)              { return __hip_atomic_load(p, __ATOMIC_RELAXED, __HIP_MEMORY_SCOPE_AGENT); }
; __device__ __forceinline__ unsigned xb_add(unsigned* p, unsigned v) { return __hip_atomic_fetch_add(p, v, __ATOMIC_RELAXED, __HIP_MEMORY_SCOPE_AGENT); }
; __device__ __forceinline__ void xcd_barrier_complete(unsigned* bar, unsigned x, unsigned& nloc, unsigned& nx) {
;     const unsigned G = gridDim.x * gridDim.y * gridDim.z;
;     unsigned sum, cnt, mine, sp = 0u;
;     for (;;) {
;         sum = 0u; cnt = 0u; mine = 0u;
; #pragma unroll
;         for (unsigned j = 0; j < 16; ++j) { const unsigned c = xb_ld(&bar[XB_XCNT(j)]); sum += c; cnt += (c > 0u) ? 1u : 0u; mine = (j == x) ? c : mine; }
;         if (sum == G) break;
; __device__ __forceinline__ void xcd_barrier(const XcdBarrier& b) {
;     asm volatile("s_waitcnt vmcnt(0)" ::: "memory");
;     __syncthreads();
;     if (threadIdx.x == 0) {
;         unsigned* bar = b.bar;
;         __builtin_amdgcn_s_waitcnt(0);
;         unsigned nloc = b.st[0], nx = b.st[1];
;         if (nloc == 0u) { xcd_barrier_complete(bar, b.x, nloc, nx); b.st[0] = nloc; b.st[1] = nx; }
;         const unsigned old = xb_add(&bar[XB_XSUB(b.x)], 1u);
.LBB0_557:
	s_cmp_gt_i32 s55, 8
	s_cselect_b64 s[0:1], -1, 0
	s_and_b64 s[4:5], s[70:71], s[0:1]
	s_andn2_b64 vcc, exec, s[4:5]
	s_cbranch_vccnz .LBB0_607
	s_waitcnt vmcnt(0)
	v_cmp_eq_u32_e32 vcc, 0, v0
	s_waitcnt vmcnt(0) lgkmcnt(0)
	s_barrier
	s_and_saveexec_b64 s[4:5], vcc
	s_cbranch_execz .LBB0_606
	s_add_i32 s6, 0, 0x23fc0
	v_mov_b32_e32 v1, s6
	s_waitcnt vmcnt(0) expcnt(0) lgkmcnt(0)
	ds_read_b32 v3, v1
	s_add_i32 s6, 0, 0x23fc4
	v_mov_b32_e32 v1, s6
	ds_read_b32 v1, v1
	s_waitcnt lgkmcnt(1)
	v_cmp_ne_u32_e32 vcc, 0, v3
	s_cbranch_vccnz .LBB0_574
	v_readlane_b32 s6, v239, 0
	v_readlane_b32 s7, v239, 1
	s_load_dwordx2 s[10:11], s[6:7], 0x4
	s_add_u32 s6, s52, 0x1000
	s_addc_u32 s7, s53, 0
	s_add_u32 s8, s52, 0x1100
	s_addc_u32 s9, s53, 0
	s_waitcnt lgkmcnt(0)
	s_mul_i32 s20, s10, s3
	s_add_u32 s10, s52, 0x1200
	s_mul_i32 s20, s20, s11
	s_addc_u32 s11, s53, 0
	s_add_u32 s12, s52, 0x1300
	s_addc_u32 s13, s53, 0
	s_mov_b32 s21, 1
	v_mov_b32_e32 v17, 0
	s_branch .LBB0_562
